# plus: drop the never-taken first early-exit test in both bisection loops
# baseline (speedup 1.0000x reference)
; __device__ __forceinline__ void topk_list(const unsigned (&uk)[32], LAS int* list, LAS float* listr, LAS unsigned* listT, const GAS f32x4* sak, int lane) {
;     ...
;         const unsigned cand = T | (1u << bit);
;         int c = 0;
; #pragma unroll
;         for (int rr = 0; rr < 32; ++rr) c += __builtin_popcountll(__builtin_amdgcn_ballot_w64(uk[rr] >= cand));
;         if (c >= 256) T = cand;
;         if (c == 256) break;
.LBB0_747:
	v_lshlrev_b32_e64 v11, v10, 1
	v_or_b32_e32 v11, v11, v85
	v_cmp_ge_u32_e32 vcc, v9, v11
	s_bcnt1_i32_b64 s0, vcc
	v_cmp_ge_u32_e32 vcc, v8, v11
	s_bcnt1_i32_b64 s1, vcc
	s_add_i32 s0, s0, s1
	v_cmp_ge_u32_e32 vcc, v7, v11
	s_bcnt1_i32_b64 s1, vcc
	s_add_i32 s0, s0, s1
	v_cmp_ge_u32_e32 vcc, v6, v11
	s_bcnt1_i32_b64 s1, vcc
	s_add_i32 s0, s0, s1
	v_cmp_ge_u32_e32 vcc, v13, v11
	s_bcnt1_i32_b64 s1, vcc
	s_add_i32 s0, s0, s1
	v_cmp_ge_u32_e32 vcc, v15, v11
	s_bcnt1_i32_b64 s1, vcc
	s_add_i32 s0, s0, s1
	v_cmp_ge_u32_e32 vcc, v16, v11
	s_bcnt1_i32_b64 s1, vcc
	s_add_i32 s0, s0, s1
	v_cmp_ge_u32_e32 vcc, v18, v11
	s_bcnt1_i32_b64 s1, vcc
	s_add_i32 s0, s0, s1
	s_cmpk_le_u32 s81, 0x200
	s_cbranch_scc1 .Lbis0_tail
	v_cmp_ge_u32_e32 vcc, v145, v11
	s_bcnt1_i32_b64 s1, vcc
	s_add_i32 s0, s0, s1
	v_cmp_ge_u32_e32 vcc, v144, v11
	s_bcnt1_i32_b64 s1, vcc
	s_add_i32 s0, s0, s1
	v_cmp_ge_u32_e32 vcc, v143, v11
	s_bcnt1_i32_b64 s1, vcc
	s_add_i32 s0, s0, s1
	v_cmp_ge_u32_e32 vcc, v142, v11
	s_bcnt1_i32_b64 s1, vcc
	s_add_i32 s0, s0, s1
	s_cmpk_le_u32 s81, 0x300
	s_cbranch_scc1 .Lbis0_tail
	v_cmp_ge_u32_e32 vcc, v159, v11
	s_bcnt1_i32_b64 s1, vcc
	s_add_i32 s0, s0, s1
	v_cmp_ge_u32_e32 vcc, v158, v11
	s_bcnt1_i32_b64 s1, vcc
	s_add_i32 s0, s0, s1
	v_cmp_ge_u32_e32 vcc, v156, v11
	s_bcnt1_i32_b64 s1, vcc
	s_add_i32 s0, s0, s1
	v_cmp_ge_u32_e32 vcc, v153, v11
	s_bcnt1_i32_b64 s1, vcc
	s_add_i32 s0, s0, s1
	s_cmpk_le_u32 s81, 0x400
	s_cbranch_scc1 .Lbis0_tail
	v_cmp_ge_u32_e32 vcc, v167, v11
	s_bcnt1_i32_b64 s1, vcc
	s_add_i32 s0, s0, s1
	v_cmp_ge_u32_e32 vcc, v166, v11
	s_bcnt1_i32_b64 s1, vcc
	s_add_i32 s0, s0, s1
	v_cmp_ge_u32_e32 vcc, v165, v11
	s_bcnt1_i32_b64 s1, vcc
	s_add_i32 s0, s0, s1
	v_cmp_ge_u32_e32 vcc, v164, v11
	s_bcnt1_i32_b64 s1, vcc
	s_add_i32 s0, s0, s1
	s_cmpk_le_u32 s81, 0x500
	s_cbranch_scc1 .Lbis0_tail
	v_cmp_ge_u32_e32 vcc, v171, v11
	s_bcnt1_i32_b64 s1, vcc
	s_add_i32 s0, s0, s1
	v_cmp_ge_u32_e32 vcc, v170, v11
	s_bcnt1_i32_b64 s1, vcc
	s_add_i32 s0, s0, s1
	v_cmp_ge_u32_e32 vcc, v169, v11
	s_bcnt1_i32_b64 s1, vcc
	s_add_i32 s0, s0, s1
	v_cmp_ge_u32_e32 vcc, v168, v11
	s_bcnt1_i32_b64 s1, vcc
	s_add_i32 s0, s0, s1
	s_cmpk_le_u32 s81, 0x600
	s_cbranch_scc1 .Lbis0_tail
	v_cmp_ge_u32_e32 vcc, v175, v11
	s_bcnt1_i32_b64 s1, vcc
	s_add_i32 s0, s0, s1
	v_cmp_ge_u32_e32 vcc, v174, v11
	s_bcnt1_i32_b64 s1, vcc
	s_add_i32 s0, s0, s1
	v_cmp_ge_u32_e32 vcc, v173, v11
	s_bcnt1_i32_b64 s1, vcc
	s_add_i32 s0, s0, s1
	v_cmp_ge_u32_e32 vcc, v172, v11
	s_bcnt1_i32_b64 s1, vcc
	s_add_i32 s0, s0, s1
	s_cmpk_le_u32 s81, 0x700
	s_cbranch_scc1 .Lbis0_tail
	v_cmp_ge_u32_e32 vcc, v100, v11
	s_bcnt1_i32_b64 s1, vcc
	s_add_i32 s0, s0, s1
	v_cmp_ge_u32_e32 vcc, v89, v11
	s_bcnt1_i32_b64 s1, vcc
	s_add_i32 s0, s0, s1
	v_cmp_ge_u32_e32 vcc, v88, v11
	s_bcnt1_i32_b64 s1, vcc
	s_add_i32 s0, s0, s1
	v_cmp_ge_u32_e32 vcc, v38, v11
	s_bcnt1_i32_b64 s1, vcc
	s_add_i32 s0, s0, s1

; __device__ __forceinline__ void topk_list(const unsigned (&uk)[32], LAS int* list, LAS float* listr, LAS unsigned* listT, const GAS f32x4* sak, int lane) {
;     ...
;         const unsigned cand = T | (1u << bit);
;         int c = 0;
; #pragma unroll
;         for (int rr = 0; rr < 32; ++rr) c += __builtin_popcountll(__builtin_amdgcn_ballot_w64(uk[rr] >= cand));
;         if (c >= 256) T = cand;
;         if (c == 256) break;
.LBB0_877:
	v_lshlrev_b32_e64 v54, v5, 1
	v_or_b32_e32 v54, v54, v4
	v_cmp_ge_u32_e32 vcc, v7, v54
	s_bcnt1_i32_b64 s0, vcc
	v_cmp_ge_u32_e32 vcc, v6, v54
	s_bcnt1_i32_b64 s1, vcc
	s_add_i32 s0, s0, s1
	v_cmp_ge_u32_e32 vcc, v3, v54
	s_bcnt1_i32_b64 s1, vcc
	s_add_i32 s0, s0, s1
	v_cmp_ge_u32_e32 vcc, v2, v54
	s_bcnt1_i32_b64 s1, vcc
	s_add_i32 s0, s0, s1
	v_cmp_ge_u32_e32 vcc, v90, v54
	s_bcnt1_i32_b64 s1, vcc
	s_add_i32 s0, s0, s1
	v_cmp_ge_u32_e32 vcc, v89, v54
	s_bcnt1_i32_b64 s1, vcc
	s_add_i32 s0, s0, s1
	v_cmp_ge_u32_e32 vcc, v88, v54
	s_bcnt1_i32_b64 s1, vcc
	s_add_i32 s0, s0, s1
	v_cmp_ge_u32_e32 vcc, v87, v54
	s_bcnt1_i32_b64 s1, vcc
	s_add_i32 s0, s0, s1
	s_cmpk_le_u32 s81, 0x200
	s_cbranch_scc1 .Lbis1_tail
	v_cmp_ge_u32_e32 vcc, v120, v54
	s_bcnt1_i32_b64 s1, vcc
	s_add_i32 s0, s0, s1
	v_cmp_ge_u32_e32 vcc, v119, v54
	s_bcnt1_i32_b64 s1, vcc
	s_add_i32 s0, s0, s1
	v_cmp_ge_u32_e32 vcc, v118, v54
	s_bcnt1_i32_b64 s1, vcc
	s_add_i32 s0, s0, s1
	v_cmp_ge_u32_e32 vcc, v117, v54
	s_bcnt1_i32_b64 s1, vcc
	s_add_i32 s0, s0, s1
	s_cmpk_le_u32 s81, 0x300
	s_cbranch_scc1 .Lbis1_tail
	v_cmp_ge_u32_e32 vcc, v135, v54
	s_bcnt1_i32_b64 s1, vcc
	s_add_i32 s0, s0, s1
	v_cmp_ge_u32_e32 vcc, v134, v54
	s_bcnt1_i32_b64 s1, vcc
	s_add_i32 s0, s0, s1
	v_cmp_ge_u32_e32 vcc, v133, v54
	s_bcnt1_i32_b64 s1, vcc
	s_add_i32 s0, s0, s1
	v_cmp_ge_u32_e32 vcc, v123, v54
	s_bcnt1_i32_b64 s1, vcc
	s_add_i32 s0, s0, s1
	s_cmpk_le_u32 s81, 0x400
	s_cbranch_scc1 .Lbis1_tail
	v_cmp_ge_u32_e32 vcc, v139, v54
	s_bcnt1_i32_b64 s1, vcc
	s_add_i32 s0, s0, s1
	v_cmp_ge_u32_e32 vcc, v138, v54
	s_bcnt1_i32_b64 s1, vcc
	s_add_i32 s0, s0, s1
	v_cmp_ge_u32_e32 vcc, v137, v54
	s_bcnt1_i32_b64 s1, vcc
	s_add_i32 s0, s0, s1
	v_cmp_ge_u32_e32 vcc, v136, v54
	s_bcnt1_i32_b64 s1, vcc
	s_add_i32 s0, s0, s1
	s_cmpk_le_u32 s81, 0x500
	s_cbranch_scc1 .Lbis1_tail
	v_cmp_ge_u32_e32 vcc, v151, v54
	s_bcnt1_i32_b64 s1, vcc
	s_add_i32 s0, s0, s1
	v_cmp_ge_u32_e32 vcc, v149, v54
	s_bcnt1_i32_b64 s1, vcc
	s_add_i32 s0, s0, s1
	v_cmp_ge_u32_e32 vcc, v148, v54
	s_bcnt1_i32_b64 s1, vcc
	s_add_i32 s0, s0, s1
	v_cmp_ge_u32_e32 vcc, v147, v54
	s_bcnt1_i32_b64 s1, vcc
	s_add_i32 s0, s0, s1
	s_cmpk_le_u32 s81, 0x600
	s_cbranch_scc1 .Lbis1_tail
	v_cmp_ge_u32_e32 vcc, v163, v54
	s_bcnt1_i32_b64 s1, vcc
	s_add_i32 s0, s0, s1
	v_cmp_ge_u32_e32 vcc, v162, v54
	s_bcnt1_i32_b64 s1, vcc
	s_add_i32 s0, s0, s1
	v_cmp_ge_u32_e32 vcc, v161, v54
	s_bcnt1_i32_b64 s1, vcc
	s_add_i32 s0, s0, s1
	v_cmp_ge_u32_e32 vcc, v160, v54
	s_bcnt1_i32_b64 s1, vcc
	s_add_i32 s0, s0, s1
	s_cmpk_le_u32 s81, 0x700
	s_cbranch_scc1 .Lbis1_tail
	v_cmp_ge_u32_e32 vcc, v37, v54
	s_bcnt1_i32_b64 s1, vcc
	s_add_i32 s0, s0, s1
	v_cmp_ge_u32_e32 vcc, v36, v54
	s_bcnt1_i32_b64 s1, vcc
	s_add_i32 s0, s0, s1
	v_cmp_ge_u32_e32 vcc, v35, v54
	s_bcnt1_i32_b64 s1, vcc
	s_add_i32 s0, s0, s1
	v_cmp_ge_u32_e32 vcc, v34, v54
	s_bcnt1_i32_b64 s1, vcc
	s_add_i32 s0, s0, s1
